# grid barrier: acquire-side buffer_inv issued at arrival (waiters: before first poll; XCC leaders: after their write-back retires) instead of after the release
# speedup vs baseline: 1.0140x; 1.0140x over previous
.LBB0_135:
	s_or_b64 exec, exec, s[12:13]
	v_cvt_f32_u32_e32 v4, v2
	s_waitcnt vmcnt(0)
	v_readfirstlane_b32 s8, v3
	v_sub_u32_e32 v3, 0, v2
	v_rcp_iflag_f32_e32 v4, v4
	v_add_u32_e32 v5, s8, v1
	v_mul_f32_e32 v4, 0x4f7ffffe, v4
	v_cvt_u32_f32_e32 v4, v4
	v_mul_lo_u32 v1, v3, v4
	v_mul_hi_u32 v1, v4, v1
	v_add_u32_e32 v1, v4, v1
	v_mul_hi_u32 v1, v5, v1
	v_mul_lo_u32 v3, v1, v2
	v_sub_u32_e32 v3, v5, v3
	v_add_u32_e32 v4, 1, v1
	v_cmp_ge_u32_e32 vcc, v3, v2
	s_nop 1
	v_cndmask_b32_e32 v1, v1, v4, vcc
	v_sub_u32_e32 v4, v3, v2
	v_cndmask_b32_e32 v3, v3, v4, vcc
	v_add_u32_e32 v4, 1, v1
	v_cmp_ge_u32_e32 vcc, v3, v2
	v_add_u32_e32 v3, 1, v5
	s_nop 0
	v_cndmask_b32_e32 v1, v1, v4, vcc
	v_mul_lo_u32 v4, v2, v1
	v_add_u32_e32 v2, v4, v2
	v_cmp_ne_u32_e32 vcc, v3, v2
	s_and_saveexec_b64 s[8:9], vcc
	s_xor_b64 s[8:9], exec, s[8:9]
	s_cbranch_execz .LBB0_149
	s_waitcnt lgkmcnt(0)
	s_add_u32 s16, s92, 0xf201500
	s_addc_u32 s17, s93, 0
	v_mov_b32_e32 v0, 0
	buffer_inv sc1
	global_load_dword v0, v0, s[16:17] sc1
	s_waitcnt vmcnt(0)
	v_cmp_eq_u32_e32 vcc, v0, v1
	s_and_saveexec_b64 s[12:13], vcc
	s_cbranch_execz .LBB0_148
	s_add_u32 s14, s92, 0xf1fe200
	s_addc_u32 s15, s93, 0
	s_mov_b32 s28, 1
	s_mov_b64 s[18:19], 0
	v_mov_b32_e32 v0, 0
	s_branch .LBB0_139

.LBB0_148:
	s_or_b64 exec, exec, s[12:13]
	s_waitcnt vmcnt(0)
	s_waitcnt vmcnt(0)
.LBB0_149:
	s_andn2_saveexec_b64 s[8:9], s[8:9]
	s_cbranch_execz .LBB0_169
	s_mov_b64 s[8:9], exec
	buffer_wbl2 sc1
	s_waitcnt lgkmcnt(0)
	s_waitcnt vmcnt(0)
	buffer_inv sc1
	v_mbcnt_lo_u32_b32 v1, s8, 0
	v_mbcnt_hi_u32_b32 v1, s9, v1
	v_cmp_eq_u32_e32 vcc, 0, v1
	s_and_saveexec_b64 s[12:13], vcc
	s_cbranch_execz .LBB0_152
	s_bcnt1_i32_b64 s8, s[8:9]
	v_mov_b32_e32 v2, 0xf201000
	v_mov_b32_e32 v3, s8
	global_atomic_add v2, v2, v3, s[92:93] offset:1024 sc0

.LBB0_166:
	s_or_b64 exec, exec, s[8:9]
	s_mov_b64 s[8:9], exec
	v_mbcnt_lo_u32_b32 v0, s8, 0
	v_mbcnt_hi_u32_b32 v0, s9, v0
	v_cmp_eq_u32_e32 vcc, 0, v0
	s_waitcnt vmcnt(0)
	s_and_saveexec_b64 s[12:13], vcc
	s_cbranch_execz .LBB0_168
	s_bcnt1_i32_b64 s8, s[8:9]
	v_mov_b32_e32 v0, 0x2000
	v_mov_b32_e32 v1, s8
	global_atomic_add v0, v1, s[6:7] offset:1024

.LBB0_212:
	s_or_b64 exec, exec, s[8:9]
	v_cvt_f32_u32_e32 v4, v2
	s_waitcnt vmcnt(0)
	v_readfirstlane_b32 s6, v3
	v_sub_u32_e32 v3, 0, v2
	v_rcp_iflag_f32_e32 v4, v4
	v_add_u32_e32 v5, s6, v1
	v_mul_f32_e32 v4, 0x4f7ffffe, v4
	v_cvt_u32_f32_e32 v4, v4
	v_mul_lo_u32 v1, v3, v4
	v_mul_hi_u32 v1, v4, v1
	v_add_u32_e32 v1, v4, v1
	v_mul_hi_u32 v1, v5, v1
	v_mul_lo_u32 v3, v1, v2
	v_sub_u32_e32 v3, v5, v3
	v_add_u32_e32 v4, 1, v1
	v_cmp_ge_u32_e32 vcc, v3, v2
	s_nop 1
	v_cndmask_b32_e32 v1, v1, v4, vcc
	v_sub_u32_e32 v4, v3, v2
	v_cndmask_b32_e32 v3, v3, v4, vcc
	v_add_u32_e32 v4, 1, v1
	v_cmp_ge_u32_e32 vcc, v3, v2
	v_add_u32_e32 v3, 1, v5
	s_nop 0
	v_cndmask_b32_e32 v1, v1, v4, vcc
	v_mul_lo_u32 v4, v2, v1
	v_add_u32_e32 v2, v4, v2
	v_cmp_ne_u32_e32 vcc, v3, v2
	s_and_saveexec_b64 s[6:7], vcc
	s_xor_b64 s[6:7], exec, s[6:7]
	s_cbranch_execz .LBB0_226
	s_waitcnt lgkmcnt(0)
	s_add_u32 s14, s92, 0xf201500
	s_addc_u32 s15, s93, 0
	v_mov_b32_e32 v0, 0
	buffer_inv sc1
	global_load_dword v0, v0, s[14:15] sc1
	s_waitcnt vmcnt(0)
	v_cmp_eq_u32_e32 vcc, v0, v1
	s_and_saveexec_b64 s[8:9], vcc
	s_cbranch_execz .LBB0_225
	s_add_u32 s12, s92, 0xf1fe200
	s_addc_u32 s13, s93, 0
	s_mov_b32 s26, 1
	s_mov_b64 s[16:17], 0
	v_mov_b32_e32 v0, 0
	s_branch .LBB0_216

.LBB0_225:
	s_or_b64 exec, exec, s[8:9]
	s_waitcnt vmcnt(0)
	s_waitcnt vmcnt(0)
.LBB0_226:
	s_andn2_saveexec_b64 s[6:7], s[6:7]
	s_cbranch_execz .LBB0_246
	s_mov_b64 s[6:7], exec
	buffer_wbl2 sc1
	s_waitcnt lgkmcnt(0)
	s_waitcnt vmcnt(0)
	buffer_inv sc1
	v_mbcnt_lo_u32_b32 v1, s6, 0
	v_mbcnt_hi_u32_b32 v1, s7, v1
	v_cmp_eq_u32_e32 vcc, 0, v1
	s_and_saveexec_b64 s[8:9], vcc
	s_cbranch_execz .LBB0_229
	s_bcnt1_i32_b64 s6, s[6:7]
	v_mov_b32_e32 v2, 0xf201000
	v_mov_b32_e32 v3, s6
	global_atomic_add v2, v2, v3, s[92:93] offset:1024 sc0

.LBB0_243:
	s_or_b64 exec, exec, s[6:7]
	s_mov_b64 s[6:7], exec
	v_mbcnt_lo_u32_b32 v0, s6, 0
	v_mbcnt_hi_u32_b32 v0, s7, v0
	v_cmp_eq_u32_e32 vcc, 0, v0
	s_waitcnt vmcnt(0)
	s_and_saveexec_b64 s[8:9], vcc
	s_cbranch_execz .LBB0_245
	s_bcnt1_i32_b64 s6, s[6:7]
	v_mov_b32_e32 v0, 0x2000
	v_mov_b32_e32 v1, s6
	global_atomic_add v0, v1, s[4:5] offset:1024

.LBB0_301:
	s_or_b64 exec, exec, s[10:11]
	v_cvt_f32_u32_e32 v4, v2
	s_waitcnt vmcnt(0)
	v_readfirstlane_b32 s4, v3
	v_sub_u32_e32 v3, 0, v2
	v_rcp_iflag_f32_e32 v4, v4
	v_add_u32_e32 v5, s4, v1
	v_mul_f32_e32 v4, 0x4f7ffffe, v4
	v_cvt_u32_f32_e32 v4, v4
	v_mul_lo_u32 v1, v3, v4
	v_mul_hi_u32 v1, v4, v1
	v_add_u32_e32 v1, v4, v1
	v_mul_hi_u32 v1, v5, v1
	v_mul_lo_u32 v3, v1, v2
	v_sub_u32_e32 v3, v5, v3
	v_add_u32_e32 v4, 1, v1
	v_cmp_ge_u32_e32 vcc, v3, v2
	s_nop 1
	v_cndmask_b32_e32 v1, v1, v4, vcc
	v_sub_u32_e32 v4, v3, v2
	v_cndmask_b32_e32 v3, v3, v4, vcc
	v_add_u32_e32 v4, 1, v1
	v_cmp_ge_u32_e32 vcc, v3, v2
	v_add_u32_e32 v3, 1, v5
	s_nop 0
	v_cndmask_b32_e32 v1, v1, v4, vcc
	v_mul_lo_u32 v4, v2, v1
	v_add_u32_e32 v2, v4, v2
	v_cmp_ne_u32_e32 vcc, v3, v2
	s_and_saveexec_b64 s[4:5], vcc
	s_xor_b64 s[10:11], exec, s[4:5]
	s_cbranch_execz .LBB0_315
	v_readlane_b32 s4, v254, 16
	v_readlane_b32 s5, v254, 17
	s_waitcnt lgkmcnt(0)
	s_nop 3
	buffer_inv sc1
	global_load_dword v0, v193, s[4:5] sc1
	s_waitcnt vmcnt(0)
	v_cmp_eq_u32_e32 vcc, v0, v1
	s_and_saveexec_b64 s[16:17], vcc
	s_cbranch_execz .LBB0_314
	s_mov_b32 s4, 1
	s_mov_b64 s[18:19], 0
	s_branch .LBB0_305

.LBB0_314:
	s_or_b64 exec, exec, s[16:17]
	s_waitcnt vmcnt(0)
	s_waitcnt vmcnt(0)
.LBB0_315:
	s_andn2_saveexec_b64 s[4:5], s[10:11]
	s_cbranch_execz .LBB0_335
	s_mov_b64 s[10:11], exec
	buffer_wbl2 sc1
	s_waitcnt lgkmcnt(0)
	s_waitcnt vmcnt(0)
	buffer_inv sc1
	v_mbcnt_lo_u32_b32 v1, s10, 0
	v_mbcnt_hi_u32_b32 v1, s11, v1
	v_cmp_eq_u32_e32 vcc, 0, v1
	s_and_saveexec_b64 s[16:17], vcc
	s_cbranch_execz .LBB0_318
	s_bcnt1_i32_b64 s4, s[10:11]
	v_mov_b32_e32 v2, s4
	v_readlane_b32 s4, v254, 14
	v_readlane_b32 s5, v254, 15
	s_nop 4
	global_atomic_add v2, v193, v2, s[4:5] sc0

.LBB0_332:
	s_or_b64 exec, exec, s[10:11]
	s_mov_b64 s[10:11], exec
	v_mbcnt_lo_u32_b32 v0, s10, 0
	v_mbcnt_hi_u32_b32 v0, s11, v0
	v_cmp_eq_u32_e32 vcc, 0, v0
	s_waitcnt vmcnt(0)
	s_and_saveexec_b64 s[16:17], vcc
	s_cbranch_execz .LBB0_334
	s_bcnt1_i32_b64 s4, s[10:11]
	v_mov_b32_e32 v0, s4
	v_readlane_b32 s4, v254, 12
	v_readlane_b32 s5, v254, 13
	s_nop 4
	global_atomic_add v193, v0, s[4:5]

.LBB0_502:
	s_or_b64 exec, exec, s[10:11]
	v_cvt_f32_u32_e32 v4, v2
	s_waitcnt vmcnt(0)
	v_readfirstlane_b32 s5, v3
	v_sub_u32_e32 v3, 0, v2
	v_rcp_iflag_f32_e32 v4, v4
	v_add_u32_e32 v5, s5, v1
	v_mul_f32_e32 v4, 0x4f7ffffe, v4
	v_cvt_u32_f32_e32 v4, v4
	v_mul_lo_u32 v1, v3, v4
	v_mul_hi_u32 v1, v4, v1
	v_add_u32_e32 v1, v4, v1
	v_mul_hi_u32 v1, v5, v1
	v_mul_lo_u32 v3, v1, v2
	v_sub_u32_e32 v3, v5, v3
	v_add_u32_e32 v4, 1, v1
	v_cmp_ge_u32_e32 vcc, v3, v2
	s_nop 1
	v_cndmask_b32_e32 v1, v1, v4, vcc
	v_sub_u32_e32 v4, v3, v2
	v_cndmask_b32_e32 v3, v3, v4, vcc
	v_add_u32_e32 v4, 1, v1
	v_cmp_ge_u32_e32 vcc, v3, v2
	v_add_u32_e32 v3, 1, v5
	s_nop 0
	v_cndmask_b32_e32 v1, v1, v4, vcc
	v_mul_lo_u32 v4, v2, v1
	v_add_u32_e32 v2, v4, v2
	v_cmp_ne_u32_e32 vcc, v3, v2
	s_and_saveexec_b64 s[10:11], vcc
	s_xor_b64 s[10:11], exec, s[10:11]
	s_cbranch_execz .LBB0_516
	v_readlane_b32 s16, v254, 16
	v_readlane_b32 s17, v254, 17
	s_waitcnt lgkmcnt(0)
	s_nop 3
	buffer_inv sc1
	global_load_dword v0, v193, s[16:17] sc1
	s_waitcnt vmcnt(0)
	v_cmp_eq_u32_e32 vcc, v0, v1
	s_and_saveexec_b64 s[16:17], vcc
	s_cbranch_execz .LBB0_515
	s_mov_b32 s5, 1
	s_mov_b64 s[18:19], 0
	s_branch .LBB0_506

.LBB0_516:
	s_andn2_saveexec_b64 s[10:11], s[10:11]
	s_cbranch_execz .LBB0_536
	s_mov_b64 s[10:11], exec
	buffer_wbl2 sc1
	s_waitcnt lgkmcnt(0)
	s_waitcnt vmcnt(0)
	buffer_inv sc1
	v_mbcnt_lo_u32_b32 v1, s10, 0
	v_mbcnt_hi_u32_b32 v1, s11, v1
	v_cmp_eq_u32_e32 vcc, 0, v1
	s_and_saveexec_b64 s[16:17], vcc
	s_cbranch_execz .LBB0_519
	s_bcnt1_i32_b64 s5, s[10:11]
	v_readlane_b32 s10, v254, 14
	v_mov_b32_e32 v2, s5
	v_readlane_b32 s11, v254, 15
	s_nop 4
	global_atomic_add v2, v193, v2, s[10:11] sc0

.LBB0_533:
	s_or_b64 exec, exec, s[10:11]
	s_mov_b64 s[10:11], exec
	v_mbcnt_lo_u32_b32 v0, s10, 0
	v_mbcnt_hi_u32_b32 v0, s11, v0
	v_cmp_eq_u32_e32 vcc, 0, v0
	s_waitcnt vmcnt(0)
	s_and_saveexec_b64 s[16:17], vcc
	s_cbranch_execz .LBB0_535
	s_bcnt1_i32_b64 s5, s[10:11]
	v_readlane_b32 s10, v254, 12
	v_mov_b32_e32 v0, s5
	v_readlane_b32 s11, v254, 13
	s_nop 4
	global_atomic_add v193, v0, s[10:11]

.LBB0_1830:
	s_or_b64 exec, exec, s[10:11]
	s_mov_b64 s[10:11], exec
	v_mbcnt_lo_u32_b32 v0, s10, 0
	v_mbcnt_hi_u32_b32 v0, s11, v0
	v_cmp_eq_u32_e32 vcc, 0, v0
	s_waitcnt vmcnt(0)
	s_and_saveexec_b64 s[16:17], vcc
	s_cbranch_execz .LBB0_248
	s_bcnt1_i32_b64 s4, s[10:11]
	v_mov_b32_e32 v0, s4
	v_readlane_b32 s4, v254, 12
	v_readlane_b32 s5, v254, 13
	s_nop 4
	global_atomic_add v193, v0, s[4:5]
	s_branch .LBB0_248
